# s_setprio 1 on the waves running the decay/prefix-sum half of stage A in the output pass
# speedup vs baseline: 1.0351x; 1.0006x over previous
.LBB0_1109:
	s_mov_b64 s[12:13], -1
	s_andn2_b64 vcc, exec, s[8:9]
	s_nop 7
	v_add_f32_e32 v58, v157, v34
	v_mul_u32_u24_e32 v34, 0x410, v51
	v_add_f32_e32 v57, v157, v35
	v_add_f32_e32 v56, v157, v36
	v_add_f32_e32 v55, v157, v37
	v_add_f32_e32 v54, v157, v38
	v_add_f32_e32 v53, v157, v39
	v_add_f32_e32 v52, v157, v40
	v_add_f32_e32 v50, v157, v41
	v_add_f32_e32 v42, v157, v42
	v_add_f32_e32 v41, v157, v43
	v_add_f32_e32 v40, v157, v44
	v_add_f32_e32 v39, v157, v45
	v_add_f32_e32 v38, v157, v46
	v_add_f32_e32 v37, v157, v47
	v_add_f32_e32 v36, v157, v48
	v_add_f32_e32 v35, v157, v49
	s_cbranch_vccnz .LBB0_1111
	v_mul_f32_e32 v43, 0xbfb8aa3b, v58
	v_mul_f32_e32 v45, 0xbfb8aa3b, v57
	v_exp_f32_e32 v44, v43
	v_exp_f32_e32 v45, v45
	v_mul_f32_e32 v48, 0xbfb8aa3b, v56
	v_mul_f32_e32 v49, 0xbfb8aa3b, v55
	v_add_f32_e32 v44, 1.0, v44
	v_add_f32_e32 v45, 1.0, v45
	v_rcp_f32_e32 v44, v44
	v_rcp_f32_e32 v45, v45
	v_exp_f32_e32 v48, v48
	v_exp_f32_e32 v49, v49
	v_mul_u32_u24_e32 v43, 0x410, v51
	v_lshl_add_u32 v46, v71, 2, v43
	v_add_u32_e32 v46, 0xd180, v46
	v_add_u32_e32 v47, 0x2000, v46
	ds_write2_b32 v47, v44, v45 offset0:32 offset1:97
	v_add_f32_e32 v44, 1.0, v48
	v_add_f32_e32 v45, 1.0, v49
	v_mul_f32_e32 v48, 0xbfb8aa3b, v54
	v_mul_f32_e32 v49, 0xbfb8aa3b, v53
	v_rcp_f32_e32 v44, v44
	v_rcp_f32_e32 v45, v45
	v_exp_f32_e32 v48, v48
	v_exp_f32_e32 v49, v49
	s_mov_b64 s[12:13], 0
	ds_write2_b32 v47, v44, v45 offset0:162 offset1:227
	v_add_f32_e32 v44, 1.0, v48
	v_add_f32_e32 v45, 1.0, v49
	v_mul_f32_e32 v48, 0xbfb8aa3b, v52
	v_mul_f32_e32 v49, 0xbfb8aa3b, v50
	v_rcp_f32_e32 v44, v44
	v_rcp_f32_e32 v45, v45
	v_exp_f32_e32 v48, v48
	v_exp_f32_e32 v49, v49
	v_add_u32_e32 v47, 0x2800, v46
	ds_write2_b32 v47, v44, v45 offset0:40 offset1:105
	v_add_f32_e32 v44, 1.0, v48
	v_add_f32_e32 v45, 1.0, v49
	v_mul_f32_e32 v48, 0xbfb8aa3b, v42
	v_mul_f32_e32 v49, 0xbfb8aa3b, v41
	v_rcp_f32_e32 v44, v44
	v_rcp_f32_e32 v45, v45
	v_exp_f32_e32 v48, v48
	v_exp_f32_e32 v49, v49
	ds_write2_b32 v47, v44, v45 offset0:170 offset1:235
	v_add_f32_e32 v44, 1.0, v48
	v_add_f32_e32 v45, 1.0, v49
	v_mul_f32_e32 v48, 0xbfb8aa3b, v40
	v_mul_f32_e32 v49, 0xbfb8aa3b, v39
	v_rcp_f32_e32 v44, v44
	v_rcp_f32_e32 v45, v45
	v_exp_f32_e32 v48, v48
	v_exp_f32_e32 v49, v49
	v_add_u32_e32 v47, 0x3000, v46
	ds_write2_b32 v47, v44, v45 offset0:48 offset1:113
	v_add_f32_e32 v44, 1.0, v48
	v_add_f32_e32 v45, 1.0, v49
	v_mul_f32_e32 v48, 0xbfb8aa3b, v38
	v_rcp_f32_e32 v44, v44
	v_rcp_f32_e32 v45, v45
	v_exp_f32_e32 v48, v48
	v_mul_f32_e32 v49, 0xbfb8aa3b, v37
	v_exp_f32_e32 v49, v49
	ds_write2_b32 v47, v44, v45 offset0:178 offset1:243
	v_add_f32_e32 v44, 1.0, v48
	v_rcp_f32_e32 v45, v44
	v_add_f32_e32 v44, 1.0, v49
	v_rcp_f32_e32 v47, v44
	v_mul_f32_e32 v44, 0xbfb8aa3b, v36
	v_exp_f32_e32 v44, v44
	v_mul_f32_e32 v48, 0xbfb8aa3b, v35
	v_exp_f32_e32 v48, v48
	v_add_u32_e32 v49, 0x3800, v46
	v_add_f32_e32 v44, 1.0, v44
	v_rcp_f32_e32 v59, v44
	v_add_f32_e32 v44, 1.0, v48
	v_rcp_f32_e32 v44, v44
	ds_write2_b32 v49, v45, v47 offset0:56 offset1:121
	ds_write_b32 v46, v59 offset:15080
	.LBB0_1111:
	s_andn2_b64 vcc, exec, s[12:13]
	s_mov_b32 s12, 0xf200
	s_cbranch_vccnz .LBB0_1113
	s_setprio 1
	v_mul_f32_e32 v43, 0xbfb8aa3b, v58
	v_exp_f32_e32 v43, v43
	v_mul_f32_e32 v44, 0xbfb8aa3b, v57
	v_mul_f32_e32 v45, 0xbfb8aa3b, v56
	v_exp_f32_e32 v46, v44
	v_exp_f32_e32 v45, v45
	v_add_f32_e32 v43, 1.0, v43
	v_rcp_f32_e32 v44, v43
	v_add_f32_e32 v43, 1.0, v46
	v_rcp_f32_e32 v46, v43
	v_add_f32_e32 v43, 1.0, v45
	v_mul_f32_e32 v45, 0xbfb8aa3b, v55
	v_exp_f32_e32 v47, v45
	v_mul_f32_e32 v45, 0xbfb8aa3b, v54
	v_mul_f32_e32 v40, 0xbfb8aa3b, v40
	v_exp_f32_e32 v48, v45
	v_exp_f32_e32 v40, v40
	v_rcp_f32_e32 v45, v43
	v_add_f32_e32 v43, 1.0, v47
	v_rcp_f32_e32 v47, v43
	v_add_f32_e32 v43, 1.0, v48
	v_mul_f32_e32 v48, 0xbfb8aa3b, v53
	v_add_f32_e32 v40, 1.0, v40
	v_mul_f32_e32 v39, 0xbfb8aa3b, v39
	v_exp_f32_e32 v49, v48
	v_rcp_f32_e32 v61, v40
	v_exp_f32_e32 v40, v39
	v_mul_f32_e32 v48, 0xbfb8aa3b, v52
	v_mul_f32_e32 v42, 0xbfb8aa3b, v42
	v_mul_f32_e32 v38, 0xbfb8aa3b, v38
	v_exp_f32_e32 v53, v48
	v_rcp_f32_e32 v48, v43
	v_add_f32_e32 v43, 1.0, v49
	v_mul_f32_e32 v49, 0xbfb8aa3b, v50
	v_exp_f32_e32 v42, v42
	v_add_f32_e32 v40, 1.0, v40
	v_exp_f32_e32 v38, v38
	v_mul_f32_e32 v37, 0xbfb8aa3b, v37
	v_mul_f32_e32 v35, 0xbfb8aa3b, v35
	v_exp_f32_e32 v50, v49
	v_rcp_f32_e32 v63, v40
	v_exp_f32_e32 v40, v37
	v_mul_f32_e32 v36, 0xbfb8aa3b, v36
	v_exp_f32_e32 v35, v35
	v_exp_f32_e32 v36, v36
	v_rcp_f32_e32 v52, v43
	v_add_f32_e32 v43, 1.0, v53
	v_add_f32_e32 v42, 1.0, v42
	v_add_f32_e32 v38, 1.0, v38
	v_rcp_f32_e32 v49, v43
	v_add_f32_e32 v43, 1.0, v50
	v_rcp_f32_e32 v50, v42
	v_rcp_f32_e32 v42, v38
	v_add_f32_e32 v38, 1.0, v40
	v_add_f32_e32 v35, 1.0, v35
	v_cmp_lt_i32_e32 vcc, v153, v154
	v_pk_mul_f32 v[46:47], v[46:47], s[42:43] op_sel_hi:[1,0]
	v_rcp_f32_e32 v54, v38
	v_add_f32_e32 v36, 1.0, v36
	v_rcp_f32_e32 v55, v35
	v_cndmask_b32_e32 v35, v152, v153, vcc
	v_pk_mul_f32 v[56:57], v[44:45], s[42:43] op_sel_hi:[1,0]
	v_pk_fma_f32 v[44:45], v[44:45], s[42:43], v[46:47] op_sel_hi:[1,0,1]
	v_rcp_f32_e32 v53, v43
	v_rcp_f32_e32 v43, v36
	v_lshlrev_b32_e32 v35, 2, v35
	v_add_f32_e32 v36, v44, v45
	v_mul_f32_e32 v41, 0xbfb8aa3b, v41
	ds_bpermute_b32 v40, v35, v36
	v_exp_f32_e32 v41, v41
	v_pk_mul_f32 v[54:55], v[54:55], s[42:43] op_sel_hi:[1,0]
	v_pk_mul_f32 v[52:53], v[52:53], s[42:43] op_sel_hi:[1,0]
	v_pk_mul_f32 v[58:59], v[42:43], s[42:43] op_sel_hi:[1,0]
	v_pk_fma_f32 v[42:43], v[42:43], s[42:43], v[54:55] op_sel_hi:[1,0,1]
	v_pk_mul_f32 v[44:45], v[48:49], s[42:43] op_sel_hi:[1,0]
	v_pk_fma_f32 v[48:49], v[48:49], s[42:43], v[52:53] op_sel_hi:[1,0,1]
	v_pk_add_f32 v[42:43], v[42:43], v[42:43] op_sel:[0,1] op_sel_hi:[1,0]
	v_add_f32_e32 v41, 1.0, v41
	v_pk_add_f32 v[48:49], v[48:49], v[48:49] op_sel:[0,1] op_sel_hi:[1,0]
	s_waitcnt lgkmcnt(0)
	v_add_f32_e32 v43, 0, v40
	v_cmp_eq_u32_e32 vcc, 0, v51
	v_rcp_f32_e32 v60, v41
	ds_bpermute_b32 v38, v35, v48
	v_cndmask_b32_e64 v43, v43, 0, vcc
	v_add_f32_e32 v43, v56, v43
	v_lshl_add_u32 v56, v71, 2, v34
	v_add_f32_e32 v46, v46, v43
	v_mul_f32_e32 v62, 0xbf1b459e, v50
	ds_write2_b32 v56, v43, v46 offset1:65
	v_add_f32_e32 v43, v57, v46
	v_mul_f32_e32 v39, 0xbf1b459e, v60
	v_mul_f32_e32 v41, 0xbf1b459e, v61
	v_mul_f32_e32 v37, 0xbf1b459e, v63
	v_add_f32_e32 v46, v47, v43
	v_add_f32_e32 v40, v36, v40
	v_mov_b32_e32 v36, v1
	v_mov_b32_e32 v49, v62
	ds_write2_b32 v56, v43, v46 offset0:130 offset1:195
	s_waitcnt lgkmcnt(2)
	v_cndmask_b32_e64 v43, v38, 0, vcc
	v_pk_add_f32 v[36:37], v[40:41], v[36:37]
	v_pk_add_f32 v[38:39], v[48:49], v[38:39]
	ds_bpermute_b32 v42, v35, v42
	v_pk_add_f32 v[38:39], v[38:39], v[36:37]
	ds_bpermute_b32 v35, v35, v39
	v_add_f32_e32 v36, v36, v43
	v_add_f32_e32 v36, v44, v36
	v_add_f32_e32 v37, v52, v36
	v_add_u32_e32 v40, 0x800, v56
	ds_write2_b32 v40, v36, v37 offset0:8 offset1:73
	v_add_f32_e32 v36, v45, v37
	v_add_f32_e32 v37, v53, v36
	ds_write2_b32 v40, v36, v37 offset0:138 offset1:203
	s_waitcnt lgkmcnt(2)
	v_cndmask_b32_e64 v36, v35, 0, vcc
	v_add_f32_e32 v36, v38, v36
	v_fmac_f32_e32 v36, 0xbf1b459e, v50
	v_fmamk_f32 v37, v60, 0xbf1b459e, v36
	v_add_u32_e32 v40, 0x1000, v56
	ds_write2_b32 v40, v36, v37 offset0:16 offset1:81
	v_fmac_f32_e32 v37, 0xbf1b459e, v61
	v_fmamk_f32 v36, v63, 0xbf1b459e, v37
	v_add_f32_e32 v35, v39, v35
	ds_write2_b32 v40, v37, v36 offset0:146 offset1:211
	v_add_f32_e32 v35, v38, v35
	v_cndmask_b32_e64 v36, v42, 0, vcc
	v_add_f32_e32 v35, v35, v36
	v_add_f32_e32 v35, v58, v35
	v_add_f32_e32 v36, v54, v35
	v_add_u32_e32 v37, 0x1800, v56
	ds_write2_b32 v37, v35, v36 offset0:24 offset1:89
	v_add_f32_e32 v35, v59, v36
	s_mov_b32 s12, 0
	v_add_f32_e32 v44, v55, v35
	v_mov_b32_e32 v43, v34
	ds_write_b32 v56, v35 offset:6760
	.LBB0_1113:
	s_setprio 0
	v_lshlrev_b32_e32 v144, 2, v71
	v_add3_u32 v34, s12, v144, v43
	v_and_b32_e32 v73, 7, v141
	ds_write_b32 v34, v44 offset:7020
	s_branch .La_join_b
